# overlapped final norm now split over both CUs of each pair (128 rows each, 8 waves); the K-lo CUs join it after their tile
# speedup vs baseline: 1.0097x; 1.0028x over previous
.Lw10d:
	v_readlane_b32 s2, v254, 6
	v_readlane_b32 s3, v254, 7
	v_and_b32_e32 v0, 63, v210
	v_readfirstlane_b32 s0, v210
	v_lshlrev_b32_e32 v1, 3, v0
	v_lshlrev_b32_e32 v2, 4, v0
	v_mov_b32_e32 v3, 0x3a800000
	v_mov_b32_e32 v121, 0x358637bd
	s_lshr_b32 s0, s0, 6
	global_load_dwordx4 v[4:7], v2, s[2:3]
	global_load_dwordx4 v[8:11], v2, s[2:3] offset:1024
	global_load_dwordx4 v[12:15], v2, s[2:3] offset:2048
	global_load_dwordx4 v[16:19], v2, s[2:3] offset:3072
	s_and_b32 s1, s101, 0x7f
	s_and_b32 s4, s1, 7
	s_lshr_b32 s5, s1, 4
	s_cmp_lt_u32 s4, 4
	s_cselect_b32 s4, 4, 0xff
	s_cmp_eq_u32 s5, s4
	s_cbranch_scc1 .Lp10a_done
	s_and_b32 s4, s1, 7
	s_mul_i32 s4, s4, 20
	s_lshr_b32 s5, s1, 3
	s_add_i32 s4, s4, s5
	s_lshl_b32 s4, s4, 8
	s_cmp_gt_u32 s0, 7
	s_cbranch_scc1 .Lp10a_done
	s_lshl_b32 s5, s0, 4
	s_lshr_b32 s11, s101, 7
	s_lshl_b32 s11, s11, 7
	s_add_i32 s5, s5, s11
	s_add_i32 s4, s4, s5
	s_movk_i32 s10, 4
	s_lshl_b32 s5, s4, 11
	s_add_u32 s12, s78, s5
	s_addc_u32 s13, s79, 0
	s_add_u32 s12, s12, 0x2000000
	s_addc_u32 s13, s13, 0
	s_lshl_b32 s5, s4, 12
	s_add_u32 s14, s76, s5
	s_addc_u32 s15, s77, 0

.Lp9_to_seam9:
	s_cmp_eq_u32 s96, 1
	s_cbranch_scc0 .Lp9_ts9
	s_mov_b32 s96, 3
	s_branch .Lp10a
